# attention fast loops: raise wave priority during the MFMA burst
# speedup vs baseline: 1.0438x; 1.0027x over previous
; __device__ __forceinline__ void attn_unit(KP P, LAS unsigned char* lds, int l, int tid, int b, int hh, int q0, bool lat) {
;     ...
;         if (__any(pend != 0.f)) { S0 = S0 - pend; S1 = S1 - pend; }
;         AT_QK_LD((s + 1) & 1);
;         __builtin_amdgcn_sched_barrier(0);
;         __builtin_amdgcn_s_setprio(1); AT_QK_MMA(N0, N1); __builtin_amdgcn_s_setprio(0);
;         AT_PV_LD(vs_prev);
;         __builtin_amdgcn_sched_barrier(0);
;         __builtin_amdgcn_s_setprio(1); AT_PV_MMA(); __builtin_amdgcn_s_setprio(0);
;         __builtin_amdgcn_sched_barrier(0);
;         float rm = __builtin_fmaxf(__builtin_fmaxf(S0[0], S1[0]), S0[1]);
; #pragma unroll
;         for (int r = 1; r < 16; ++r) rm = __builtin_fmaxf(__builtin_fmaxf(rm, S1[r]), r < 15 ? S0[r + 1] : S1[r]);
;         { const auto rr = __builtin_amdgcn_permlane32_swap(__float_as_uint(rm), __float_as_uint(rm), false, false); rm = fmaxf(__uint_as_float(rr[0]), __uint_as_float(rr[1])); }
;         float alpha = 1.f; pend = 0.f;
;         if (s == 0 || __any(rm > AT_THR)) {
;             const float dl = s == 0 ? rm : fmaxf(rm, 0.f);
;             S0 = S0 - dl; S1 = S1 - dl; negm = negm - dl; m += dl; pend = dl;
;             alpha = __builtin_amdgcn_exp2f(-dl); lsum *= alpha;
;         }
;         float ps = 0.f;
; #pragma unroll
;         for (int r = 0; r < 16; ++r) { S0[r] = __builtin_amdgcn_exp2f(S0[r]); S1[r] = __builtin_amdgcn_exp2f(S1[r]); ps += S0[r] + S1[r]; }
;         lsum += ps;
; #pragma unroll
;         for (int sl = 0; sl < 4; ++sl) { const int rb = 8 * (sl & 1);
;             if (sl < 2) pp[sl] = (u32x4_t){cvtpk(S0[rb], S0[rb + 1]), cvtpk(S0[rb + 2], S0[rb + 3]), cvtpk(S0[rb + 4], S0[rb + 5]), cvtpk(S0[rb + 6], S0[rb + 7])};
;             else pp[sl] = (u32x4_t){cvtpk(S1[rb], S1[rb + 1]), cvtpk(S1[rb + 2], S1[rb + 3]), cvtpk(S1[rb + 4], S1[rb + 5]), cvtpk(S1[rb + 6], S1[rb + 7])}; }
;         __builtin_amdgcn_sched_barrier(0);
;         if (__any(alpha != 1.f)) {
; #pragma unroll
;             for (int r = 0; r < 16; ++r) { O0[r] *= alpha; O1[r] *= alpha; } }
;         if (s + 2 < nsteps) AT_STOREK(s & 1);
;         if (s + 1 < nsteps) AT_STOREV(vs_next);
;         __syncthreads();
;         S0 = N0; S1 = N1;
;         vs_prev = vs_cur; vs_cur = vs_next; vs_next = vs_next == 2 ? 0 : vs_next + 1;
;     }
.Lat0_A:
	s_mul_i32 s54, s57, 0x4400
	v_add_u32_e32 v218, s54, v175
	ds_read_b128 v[200:203], v177 offset:16384
	ds_read_b128 v[204:207], v177 offset:20480
	ds_read_b128 v[208:211], v194 offset:16384
	ds_read_b128 v[212:215], v194 offset:20480
	ds_read_b128 v[226:229], v195 offset:16384
	ds_read_b128 v[230:233], v195 offset:20480
	ds_read_b128 v[234:237], v196 offset:16384
	ds_read_b128 v[238:241], v196 offset:20480
	s_setprio 1
	s_waitcnt lgkmcnt(7)
	v_mfma_f32_32x32x16_bf16 v[80:95], v[200:203], v[128:131], v[32:47]
	s_waitcnt lgkmcnt(6)
	v_mfma_f32_32x32x16_bf16 v[96:111], v[204:207], v[128:131], v[32:47]
	s_mul_i32 s55, s51, 0x4400
	ds_read_b128 v[200:203], v218 offset:32768
	s_waitcnt lgkmcnt(6)
	v_mfma_f32_32x32x16_bf16 v[80:95], v[208:211], v[132:135], v[80:95]
	v_add_u32_e32 v219, s55, v192
	ds_read_b128 v[204:207], v218 offset:41472
	s_waitcnt lgkmcnt(6)
	v_mfma_f32_32x32x16_bf16 v[96:111], v[212:215], v[132:135], v[96:111]
	s_add_i32 s54, s26, s50
	ds_read_b128 v[208:211], v218 offset:32800
	s_waitcnt lgkmcnt(6)
	v_mfma_f32_32x32x16_bf16 v[80:95], v[226:229], v[136:139], v[80:95]
	s_add_i32 s22, s56, 3
	ds_read_b128 v[212:215], v218 offset:41504
	s_waitcnt lgkmcnt(6)
	v_mfma_f32_32x32x16_bf16 v[96:111], v[230:233], v[136:139], v[96:111]
	s_nop 0
	ds_read_b128 v[226:229], v218 offset:32832
	s_waitcnt lgkmcnt(6)
	v_mfma_f32_32x32x16_bf16 v[80:95], v[234:237], v[140:143], v[80:95]
	s_nop 0
	ds_read_b128 v[230:233], v218 offset:41536
	s_waitcnt vmcnt(2)
	ds_write_b128 v191, v[112:115] offset:0
	ds_write_b128 v191, v[116:119] offset:8192
	s_waitcnt lgkmcnt(8)
	v_mfma_f32_32x32x16_bf16 v[96:111], v[238:241], v[140:143], v[96:111]
	s_nop 0
	ds_read_b128 v[234:237], v218 offset:32864
	s_waitcnt vmcnt(0)
	ds_write_b64 v219, v[120:121] offset:32768
	ds_write_b64 v219, v[122:123] offset:32784
	ds_read_b128 v[238:241], v218 offset:41568
	ds_write_b64 v219, v[124:125] offset:41472
	ds_write_b64 v219, v[126:127] offset:41488
	s_waitcnt lgkmcnt(13)
	v_mfma_f32_32x32x16_bf16 v[0:15], v[200:203], v[148:151], v[0:15]
	s_cmp_lt_i32 s22, s48
	s_cbranch_scc0 .Lat0_A_nok
	s_add_i32 s30, s54, 0x180
	s_ashr_i32 s31, s30, 31
	s_lshl_b64 s[30:31], s[30:31], 8
	v_lshl_add_u64 v[184:185], v[180:181], 0, s[30:31]
	global_load_dwordx4 v[112:115], v[184:185], off
	s_add_i32 s30, s54, 0x1c0
	s_ashr_i32 s31, s30, 31
	s_lshl_b64 s[30:31], s[30:31], 8
	v_lshl_add_u64 v[184:185], v[180:181], 0, s[30:31]
	global_load_dwordx4 v[116:119], v[184:185], off
.Lat0_A_nok:
	s_waitcnt lgkmcnt(12)
	v_mfma_f32_32x32x16_bf16 v[16:31], v[204:207], v[148:151], v[16:31]
	s_add_i32 s58, s54, 0x100
	s_ashr_i32 s59, s58, 31
	s_lshl_b64 s[58:59], s[58:59], 1
	v_lshl_add_u64 v[184:185], v[182:183], 0, s[58:59]
	global_load_dwordx4 v[120:123], v[184:185], off
	s_waitcnt lgkmcnt(11)
	v_mfma_f32_32x32x16_bf16 v[0:15], v[208:211], v[156:159], v[0:15]
	s_add_u32 s58, s58, 0x84000
	s_addc_u32 s59, s59, 0
	v_lshl_add_u64 v[184:185], v[182:183], 0, s[58:59]
	global_load_dwordx4 v[124:127], v[184:185], off
	s_waitcnt lgkmcnt(10)
	v_mfma_f32_32x32x16_bf16 v[16:31], v[212:215], v[156:159], v[16:31]
	s_waitcnt lgkmcnt(9)
	v_mfma_f32_32x32x16_bf16 v[0:15], v[226:229], v[152:155], v[0:15]
	s_waitcnt lgkmcnt(8)
	v_mfma_f32_32x32x16_bf16 v[16:31], v[230:233], v[152:155], v[16:31]
	s_waitcnt lgkmcnt(5)
	v_mfma_f32_32x32x16_bf16 v[0:15], v[234:237], v[144:147], v[0:15]
	s_waitcnt lgkmcnt(2)
	v_mfma_f32_32x32x16_bf16 v[16:31], v[238:241], v[144:147], v[16:31]
	s_setprio 0
	v_exp_f32_e32 v64, v64
	v_exp_f32_e32 v48, v48
	v_exp_f32_e32 v65, v65
	v_exp_f32_e32 v49, v49
	v_exp_f32_e32 v66, v66
	v_exp_f32_e32 v50, v50
	v_exp_f32_e32 v67, v67
	v_exp_f32_e32 v51, v51
	v_add_f32_e32 v220, v48, v64
	v_exp_f32_e32 v68, v68
	v_exp_f32_e32 v52, v52
	v_add_f32_e32 v221, v49, v65
	v_add_f32_e32 v220, v221, v220
	v_exp_f32_e32 v69, v69
	v_exp_f32_e32 v53, v53
	v_add_f32_e32 v221, v50, v66
	v_add_f32_e32 v220, v221, v220
	v_exp_f32_e32 v70, v70
	v_exp_f32_e32 v54, v54
	v_add_f32_e32 v221, v51, v67
	v_add_f32_e32 v220, v221, v220
	v_exp_f32_e32 v71, v71
	v_exp_f32_e32 v55, v55
	v_add_f32_e32 v221, v52, v68
	v_add_f32_e32 v220, v221, v220
	v_exp_f32_e32 v72, v72
	v_exp_f32_e32 v56, v56
	v_add_f32_e32 v221, v53, v69
	v_add_f32_e32 v220, v221, v220
	v_exp_f32_e32 v73, v73
	v_exp_f32_e32 v57, v57
	v_add_f32_e32 v221, v54, v70
	v_add_f32_e32 v220, v221, v220
	v_exp_f32_e32 v74, v74
	v_exp_f32_e32 v58, v58
	v_add_f32_e32 v221, v55, v71
	v_add_f32_e32 v220, v221, v220
	v_exp_f32_e32 v75, v75
	v_exp_f32_e32 v59, v59
	v_add_f32_e32 v221, v56, v72
	v_add_f32_e32 v220, v221, v220
	v_exp_f32_e32 v76, v76
	v_exp_f32_e32 v60, v60
	v_add_f32_e32 v221, v57, v73
	v_add_f32_e32 v220, v221, v220
	v_exp_f32_e32 v77, v77
	v_exp_f32_e32 v61, v61
	v_add_f32_e32 v221, v58, v74
	v_add_f32_e32 v220, v221, v220
	v_exp_f32_e32 v78, v78
	v_exp_f32_e32 v62, v62
	v_add_f32_e32 v221, v59, v75
	v_add_f32_e32 v220, v221, v220
	v_exp_f32_e32 v79, v79
	v_exp_f32_e32 v63, v63
	v_add_f32_e32 v221, v60, v76
	v_add_f32_e32 v220, v221, v220
	v_add_f32_e32 v221, v61, v77
	v_add_f32_e32 v220, v221, v220
	v_add_f32_e32 v221, v62, v78
	v_add_f32_e32 v220, v221, v220
	v_add_f32_e32 v221, v63, v79
	v_add_f32_e32 v220, v221, v220
	v_add_f32_e32 v197, v197, v220
	v_cvt_pk_bf16_f32 v148, v64, v65
	v_cvt_pk_bf16_f32 v149, v66, v67
	v_cvt_pk_bf16_f32 v150, v68, v69
	v_cvt_pk_bf16_f32 v151, v70, v71
	v_cvt_pk_bf16_f32 v156, v72, v73
	v_cvt_pk_bf16_f32 v157, v74, v75
	v_cvt_pk_bf16_f32 v158, v76, v77
	v_cvt_pk_bf16_f32 v159, v78, v79
	v_cvt_pk_bf16_f32 v152, v48, v49
	v_cvt_pk_bf16_f32 v153, v50, v51
	v_cvt_pk_bf16_f32 v154, v52, v53
	v_cvt_pk_bf16_f32 v155, v54, v55
	v_cvt_pk_bf16_f32 v144, v56, v57
	v_cvt_pk_bf16_f32 v145, v58, v59
	v_cvt_pk_bf16_f32 v146, v60, v61
	v_cvt_pk_bf16_f32 v147, v62, v63
	v_max3_f32 v242, v80, v81, v82
	v_max3_f32 v242, v242, v83, v84
	v_max3_f32 v242, v242, v85, v86
	v_max3_f32 v242, v242, v87, v88
	v_max3_f32 v242, v242, v89, v90
	v_max3_f32 v242, v242, v91, v92
	v_max3_f32 v242, v242, v93, v94
	v_max3_f32 v242, v242, v95, v96
	v_max3_f32 v242, v242, v97, v98
	v_max3_f32 v242, v242, v99, v100
	v_max3_f32 v242, v242, v101, v102
	v_max3_f32 v242, v242, v103, v104
	v_max3_f32 v242, v242, v105, v106
	v_max3_f32 v242, v242, v107, v108
	v_max3_f32 v242, v242, v109, v110
	v_max_f32_e32 v242, v242, v111
	v_cmp_lt_f32_e32 vcc, 0x41000000, v242
	s_add_i32 s53, s53, 0x4000
	s_mov_b32 s57, s52
	s_mov_b32 s52, s51
	s_add_i32 s22, s51, 1
	s_cmp_lg_u32 s51, 2
	s_cselect_b32 s51, s22, 0
	s_add_i32 s56, s56, 1
	s_addk_i32 s50, 0x80
	s_waitcnt lgkmcnt(0)
	s_barrier
	s_cbranch_vccnz .Lat_exitA
; __device__ __forceinline__ void attn_unit(KP P, LAS unsigned char* lds, int l, int tid, int b, int hh, int q0, bool lat) {
;     ...
;         if (__any(pend != 0.f)) { S0 = S0 - pend; S1 = S1 - pend; }
;         AT_QK_LD((s + 1) & 1);
;         __builtin_amdgcn_sched_barrier(0);
;         __builtin_amdgcn_s_setprio(1); AT_QK_MMA(N0, N1); __builtin_amdgcn_s_setprio(0);
;         AT_PV_LD(vs_prev);
;         __builtin_amdgcn_sched_barrier(0);
;         __builtin_amdgcn_s_setprio(1); AT_PV_MMA(); __builtin_amdgcn_s_setprio(0);
;         __builtin_amdgcn_sched_barrier(0);
;         float rm = __builtin_fmaxf(__builtin_fmaxf(S0[0], S1[0]), S0[1]);
; #pragma unroll
;         for (int r = 1; r < 16; ++r) rm = __builtin_fmaxf(__builtin_fmaxf(rm, S1[r]), r < 15 ? S0[r + 1] : S1[r]);
;         { const auto rr = __builtin_amdgcn_permlane32_swap(__float_as_uint(rm), __float_as_uint(rm), false, false); rm = fmaxf(__uint_as_float(rr[0]), __uint_as_float(rr[1])); }
;         float alpha = 1.f; pend = 0.f;
;         if (s == 0 || __any(rm > AT_THR)) {
;             const float dl = s == 0 ? rm : fmaxf(rm, 0.f);
;             S0 = S0 - dl; S1 = S1 - dl; negm = negm - dl; m += dl; pend = dl;
;             alpha = __builtin_amdgcn_exp2f(-dl); lsum *= alpha;
;         }
;         float ps = 0.f;
; #pragma unroll
;         for (int r = 0; r < 16; ++r) { S0[r] = __builtin_amdgcn_exp2f(S0[r]); S1[r] = __builtin_amdgcn_exp2f(S1[r]); ps += S0[r] + S1[r]; }
;         lsum += ps;
; #pragma unroll
;         for (int sl = 0; sl < 4; ++sl) { const int rb = 8 * (sl & 1);
;             if (sl < 2) pp[sl] = (u32x4_t){cvtpk(S0[rb], S0[rb + 1]), cvtpk(S0[rb + 2], S0[rb + 3]), cvtpk(S0[rb + 4], S0[rb + 5]), cvtpk(S0[rb + 6], S0[rb + 7])};
;             else pp[sl] = (u32x4_t){cvtpk(S1[rb], S1[rb + 1]), cvtpk(S1[rb + 2], S1[rb + 3]), cvtpk(S1[rb + 4], S1[rb + 5]), cvtpk(S1[rb + 6], S1[rb + 7])}; }
;         __builtin_amdgcn_sched_barrier(0);
;         if (__any(alpha != 1.f)) {
; #pragma unroll
;             for (int r = 0; r < 16; ++r) { O0[r] *= alpha; O1[r] *= alpha; } }
;         if (s + 2 < nsteps) AT_STOREK(s & 1);
;         if (s + 1 < nsteps) AT_STOREV(vs_next);
;         __syncthreads();
;         S0 = N0; S1 = N1;
;         vs_prev = vs_cur; vs_cur = vs_next; vs_next = vs_next == 2 ? 0 : vs_next + 1;
;     }
.Lat0_B:
	s_mul_i32 s54, s57, 0x4400
	v_add_u32_e32 v218, s54, v175
	ds_read_b128 v[200:203], v177 offset:0
	ds_read_b128 v[204:207], v177 offset:4096
	ds_read_b128 v[208:211], v194 offset:0
	ds_read_b128 v[212:215], v194 offset:4096
	ds_read_b128 v[226:229], v195 offset:0
	ds_read_b128 v[230:233], v195 offset:4096
	ds_read_b128 v[234:237], v196 offset:0
	ds_read_b128 v[238:241], v196 offset:4096
	s_setprio 1
	s_waitcnt lgkmcnt(7)
	v_mfma_f32_32x32x16_bf16 v[64:79], v[200:203], v[128:131], v[32:47]
	s_waitcnt lgkmcnt(6)
	v_mfma_f32_32x32x16_bf16 v[48:63], v[204:207], v[128:131], v[32:47]
	s_mul_i32 s55, s51, 0x4400
	ds_read_b128 v[200:203], v218 offset:32768
	s_waitcnt lgkmcnt(6)
	v_mfma_f32_32x32x16_bf16 v[64:79], v[208:211], v[132:135], v[64:79]
	v_add_u32_e32 v219, s55, v192
	ds_read_b128 v[204:207], v218 offset:41472
	s_waitcnt lgkmcnt(6)
	v_mfma_f32_32x32x16_bf16 v[48:63], v[212:215], v[132:135], v[48:63]
	s_add_i32 s54, s26, s50
	ds_read_b128 v[208:211], v218 offset:32800
	s_waitcnt lgkmcnt(6)
	v_mfma_f32_32x32x16_bf16 v[64:79], v[226:229], v[136:139], v[64:79]
	s_add_i32 s22, s56, 3
	ds_read_b128 v[212:215], v218 offset:41504
	s_waitcnt lgkmcnt(6)
	v_mfma_f32_32x32x16_bf16 v[48:63], v[230:233], v[136:139], v[48:63]
	s_nop 0
	ds_read_b128 v[226:229], v218 offset:32832
	s_waitcnt lgkmcnt(6)
	v_mfma_f32_32x32x16_bf16 v[64:79], v[234:237], v[140:143], v[64:79]
	s_nop 0
	ds_read_b128 v[230:233], v218 offset:41536
	s_waitcnt vmcnt(2)
	ds_write_b128 v191, v[112:115] offset:16384
	ds_write_b128 v191, v[116:119] offset:24576
	s_waitcnt lgkmcnt(8)
	v_mfma_f32_32x32x16_bf16 v[48:63], v[238:241], v[140:143], v[48:63]
	s_nop 0
	ds_read_b128 v[234:237], v218 offset:32864
	s_waitcnt vmcnt(0)
	ds_write_b64 v219, v[120:121] offset:32768
	ds_write_b64 v219, v[122:123] offset:32784
	ds_read_b128 v[238:241], v218 offset:41568
	ds_write_b64 v219, v[124:125] offset:41472
	ds_write_b64 v219, v[126:127] offset:41488
	s_waitcnt lgkmcnt(13)
	v_mfma_f32_32x32x16_bf16 v[0:15], v[200:203], v[148:151], v[0:15]
	s_cmp_lt_i32 s22, s48
	s_cbranch_scc0 .Lat0_B_nok
	s_add_i32 s30, s54, 0x180
	s_ashr_i32 s31, s30, 31
	s_lshl_b64 s[30:31], s[30:31], 8
	v_lshl_add_u64 v[184:185], v[180:181], 0, s[30:31]
	global_load_dwordx4 v[112:115], v[184:185], off
	s_add_i32 s30, s54, 0x1c0
	s_ashr_i32 s31, s30, 31
	s_lshl_b64 s[30:31], s[30:31], 8
	v_lshl_add_u64 v[184:185], v[180:181], 0, s[30:31]
	global_load_dwordx4 v[116:119], v[184:185], off
.Lat0_B_nok:
	s_waitcnt lgkmcnt(12)
	v_mfma_f32_32x32x16_bf16 v[16:31], v[204:207], v[148:151], v[16:31]
	s_add_i32 s58, s54, 0x100
	s_ashr_i32 s59, s58, 31
	s_lshl_b64 s[58:59], s[58:59], 1
	v_lshl_add_u64 v[184:185], v[182:183], 0, s[58:59]
	global_load_dwordx4 v[120:123], v[184:185], off
	s_waitcnt lgkmcnt(11)
	v_mfma_f32_32x32x16_bf16 v[0:15], v[208:211], v[156:159], v[0:15]
	s_add_u32 s58, s58, 0x84000
	s_addc_u32 s59, s59, 0
	v_lshl_add_u64 v[184:185], v[182:183], 0, s[58:59]
	global_load_dwordx4 v[124:127], v[184:185], off
	s_waitcnt lgkmcnt(10)
	v_mfma_f32_32x32x16_bf16 v[16:31], v[212:215], v[156:159], v[16:31]
	s_waitcnt lgkmcnt(9)
	v_mfma_f32_32x32x16_bf16 v[0:15], v[226:229], v[152:155], v[0:15]
	s_waitcnt lgkmcnt(8)
	v_mfma_f32_32x32x16_bf16 v[16:31], v[230:233], v[152:155], v[16:31]
	s_waitcnt lgkmcnt(5)
	v_mfma_f32_32x32x16_bf16 v[0:15], v[234:237], v[144:147], v[0:15]
	s_waitcnt lgkmcnt(2)
	v_mfma_f32_32x32x16_bf16 v[16:31], v[238:241], v[144:147], v[16:31]
	s_setprio 0
	v_exp_f32_e32 v80, v80
	v_exp_f32_e32 v96, v96
	v_exp_f32_e32 v81, v81
	v_exp_f32_e32 v97, v97
	v_exp_f32_e32 v82, v82
	v_exp_f32_e32 v98, v98
	v_exp_f32_e32 v83, v83
	v_exp_f32_e32 v99, v99
	v_add_f32_e32 v220, v96, v80
	v_exp_f32_e32 v84, v84
	v_exp_f32_e32 v100, v100
	v_add_f32_e32 v221, v97, v81
	v_add_f32_e32 v220, v221, v220
	v_exp_f32_e32 v85, v85
	v_exp_f32_e32 v101, v101
	v_add_f32_e32 v221, v98, v82
	v_add_f32_e32 v220, v221, v220
	v_exp_f32_e32 v86, v86
	v_exp_f32_e32 v102, v102
	v_add_f32_e32 v221, v99, v83
	v_add_f32_e32 v220, v221, v220
	v_exp_f32_e32 v87, v87
	v_exp_f32_e32 v103, v103
	v_add_f32_e32 v221, v100, v84
	v_add_f32_e32 v220, v221, v220
	v_exp_f32_e32 v88, v88
	v_exp_f32_e32 v104, v104
	v_add_f32_e32 v221, v101, v85
	v_add_f32_e32 v220, v221, v220
	v_exp_f32_e32 v89, v89
	v_exp_f32_e32 v105, v105
	v_add_f32_e32 v221, v102, v86
	v_add_f32_e32 v220, v221, v220
	v_exp_f32_e32 v90, v90
	v_exp_f32_e32 v106, v106
	v_add_f32_e32 v221, v103, v87
	v_add_f32_e32 v220, v221, v220
	v_exp_f32_e32 v91, v91
	v_exp_f32_e32 v107, v107
	v_add_f32_e32 v221, v104, v88
	v_add_f32_e32 v220, v221, v220
	v_exp_f32_e32 v92, v92
	v_exp_f32_e32 v108, v108
	v_add_f32_e32 v221, v105, v89
	v_add_f32_e32 v220, v221, v220
	v_exp_f32_e32 v93, v93
	v_exp_f32_e32 v109, v109
	v_add_f32_e32 v221, v106, v90
	v_add_f32_e32 v220, v221, v220
	v_exp_f32_e32 v94, v94
	v_exp_f32_e32 v110, v110
	v_add_f32_e32 v221, v107, v91
	v_add_f32_e32 v220, v221, v220
	v_exp_f32_e32 v95, v95
	v_exp_f32_e32 v111, v111
	v_add_f32_e32 v221, v108, v92
	v_add_f32_e32 v220, v221, v220
	v_add_f32_e32 v221, v109, v93
	v_add_f32_e32 v220, v221, v220
	v_add_f32_e32 v221, v110, v94
	v_add_f32_e32 v220, v221, v220
	v_add_f32_e32 v221, v111, v95
	v_add_f32_e32 v220, v221, v220
	v_add_f32_e32 v197, v197, v220
	v_cvt_pk_bf16_f32 v148, v80, v81
	v_cvt_pk_bf16_f32 v149, v82, v83
	v_cvt_pk_bf16_f32 v150, v84, v85
	v_cvt_pk_bf16_f32 v151, v86, v87
	v_cvt_pk_bf16_f32 v156, v88, v89
	v_cvt_pk_bf16_f32 v157, v90, v91
	v_cvt_pk_bf16_f32 v158, v92, v93
	v_cvt_pk_bf16_f32 v159, v94, v95
	v_cvt_pk_bf16_f32 v152, v96, v97
	v_cvt_pk_bf16_f32 v153, v98, v99
	v_cvt_pk_bf16_f32 v154, v100, v101
	v_cvt_pk_bf16_f32 v155, v102, v103
	v_cvt_pk_bf16_f32 v144, v104, v105
	v_cvt_pk_bf16_f32 v145, v106, v107
	v_cvt_pk_bf16_f32 v146, v108, v109
	v_cvt_pk_bf16_f32 v147, v110, v111
	v_max3_f32 v242, v64, v65, v66
	v_max3_f32 v242, v242, v67, v68
	v_max3_f32 v242, v242, v69, v70
	v_max3_f32 v242, v242, v71, v72
	v_max3_f32 v242, v242, v73, v74
	v_max3_f32 v242, v242, v75, v76
	v_max3_f32 v242, v242, v77, v78
	v_max3_f32 v242, v242, v79, v48
	v_max3_f32 v242, v242, v49, v50
	v_max3_f32 v242, v242, v51, v52
	v_max3_f32 v242, v242, v53, v54
	v_max3_f32 v242, v242, v55, v56
	v_max3_f32 v242, v242, v57, v58
	v_max3_f32 v242, v242, v59, v60
	v_max3_f32 v242, v242, v61, v62
	v_max_f32_e32 v242, v242, v63
	v_cmp_lt_f32_e32 vcc, 0x41000000, v242
	s_add_i32 s53, s53, 0x4000
	s_mov_b32 s57, s52
	s_mov_b32 s52, s51
	s_add_i32 s22, s51, 1
	s_cmp_lg_u32 s51, 2
	s_cselect_b32 s51, s22, 0
	s_add_i32 s56, s56, 1
	s_addk_i32 s50, 0x80
	s_waitcnt lgkmcnt(0)
	s_barrier
	s_cbranch_vccnz .Lat_exitB
	s_cmp_lt_u32 s56, 63
	s_cbranch_scc1 .Lat0_A
	s_branch .Lat_exitB
; __device__ __forceinline__ void attn_unit(KP P, LAS unsigned char* lds, int l, int tid, int b, int hh, int q0, bool lat) {
;     ...
;         if (__any(pend != 0.f)) { S0 = S0 - pend; S1 = S1 - pend; }
;         AT_QK_LD((s + 1) & 1);
;         __builtin_amdgcn_sched_barrier(0);
;         __builtin_amdgcn_s_setprio(1); AT_QK_MMA(N0, N1); __builtin_amdgcn_s_setprio(0);
;         AT_PV_LD(vs_prev);
;         __builtin_amdgcn_sched_barrier(0);
;         __builtin_amdgcn_s_setprio(1); AT_PV_MMA(); __builtin_amdgcn_s_setprio(0);
;         __builtin_amdgcn_sched_barrier(0);
;         float rm = __builtin_fmaxf(__builtin_fmaxf(S0[0], S1[0]), S0[1]);
; #pragma unroll
;         for (int r = 1; r < 16; ++r) rm = __builtin_fmaxf(__builtin_fmaxf(rm, S1[r]), r < 15 ? S0[r + 1] : S1[r]);
;         { const auto rr = __builtin_amdgcn_permlane32_swap(__float_as_uint(rm), __float_as_uint(rm), false, false); rm = fmaxf(__uint_as_float(rr[0]), __uint_as_float(rr[1])); }
;         float alpha = 1.f; pend = 0.f;
;         if (s == 0 || __any(rm > AT_THR)) {
;             const float dl = s == 0 ? rm : fmaxf(rm, 0.f);
;             S0 = S0 - dl; S1 = S1 - dl; negm = negm - dl; m += dl; pend = dl;
;             alpha = __builtin_amdgcn_exp2f(-dl); lsum *= alpha;
;         }
;         float ps = 0.f;
; #pragma unroll
;         for (int r = 0; r < 16; ++r) { S0[r] = __builtin_amdgcn_exp2f(S0[r]); S1[r] = __builtin_amdgcn_exp2f(S1[r]); ps += S0[r] + S1[r]; }
;         lsum += ps;
; #pragma unroll
;         for (int sl = 0; sl < 4; ++sl) { const int rb = 8 * (sl & 1);
;             if (sl < 2) pp[sl] = (u32x4_t){cvtpk(S0[rb], S0[rb + 1]), cvtpk(S0[rb + 2], S0[rb + 3]), cvtpk(S0[rb + 4], S0[rb + 5]), cvtpk(S0[rb + 6], S0[rb + 7])};
;             else pp[sl] = (u32x4_t){cvtpk(S1[rb], S1[rb + 1]), cvtpk(S1[rb + 2], S1[rb + 3]), cvtpk(S1[rb + 4], S1[rb + 5]), cvtpk(S1[rb + 6], S1[rb + 7])}; }
;         __builtin_amdgcn_sched_barrier(0);
;         if (__any(alpha != 1.f)) {
; #pragma unroll
;             for (int r = 0; r < 16; ++r) { O0[r] *= alpha; O1[r] *= alpha; } }
;         if (s + 2 < nsteps) AT_STOREK(s & 1);
;         if (s + 1 < nsteps) AT_STOREV(vs_next);
;         __syncthreads();
;         S0 = N0; S1 = N1;
;         vs_prev = vs_cur; vs_cur = vs_next; vs_next = vs_next == 2 ? 0 : vs_next + 1;
;     }
.Lat1_A:
	v_exp_f32_e32 v64, v64
	v_exp_f32_e32 v48, v48
	v_exp_f32_e32 v65, v65
	v_exp_f32_e32 v49, v49
	v_exp_f32_e32 v66, v66
	v_exp_f32_e32 v50, v50
	v_exp_f32_e32 v67, v67
	v_exp_f32_e32 v51, v51
	v_add_f32_e32 v220, v48, v64
	v_exp_f32_e32 v68, v68
	v_exp_f32_e32 v52, v52
	v_add_f32_e32 v221, v49, v65
	v_add_f32_e32 v220, v221, v220
	v_exp_f32_e32 v69, v69
	v_exp_f32_e32 v53, v53
	v_add_f32_e32 v221, v50, v66
	v_add_f32_e32 v220, v221, v220
	v_exp_f32_e32 v70, v70
	v_exp_f32_e32 v54, v54
	v_add_f32_e32 v221, v51, v67
	v_add_f32_e32 v220, v221, v220
	v_exp_f32_e32 v71, v71
	v_exp_f32_e32 v55, v55
	v_add_f32_e32 v221, v52, v68
	v_add_f32_e32 v220, v221, v220
	v_exp_f32_e32 v72, v72
	v_exp_f32_e32 v56, v56
	v_add_f32_e32 v221, v53, v69
	v_add_f32_e32 v220, v221, v220
	v_exp_f32_e32 v73, v73
	v_exp_f32_e32 v57, v57
	v_add_f32_e32 v221, v54, v70
	v_add_f32_e32 v220, v221, v220
	v_exp_f32_e32 v74, v74
	v_exp_f32_e32 v58, v58
	v_add_f32_e32 v221, v55, v71
	v_add_f32_e32 v220, v221, v220
	v_exp_f32_e32 v75, v75
	v_exp_f32_e32 v59, v59
	v_add_f32_e32 v221, v56, v72
	v_add_f32_e32 v220, v221, v220
	v_exp_f32_e32 v76, v76
	v_exp_f32_e32 v60, v60
	v_add_f32_e32 v221, v57, v73
	v_add_f32_e32 v220, v221, v220
	v_exp_f32_e32 v77, v77
	v_exp_f32_e32 v61, v61
	v_add_f32_e32 v221, v58, v74
	v_add_f32_e32 v220, v221, v220
	v_exp_f32_e32 v78, v78
	v_exp_f32_e32 v62, v62
	v_add_f32_e32 v221, v59, v75
	v_add_f32_e32 v220, v221, v220
	v_exp_f32_e32 v79, v79
	v_exp_f32_e32 v63, v63
	v_add_f32_e32 v221, v60, v76
	v_add_f32_e32 v220, v221, v220
	v_add_f32_e32 v221, v61, v77
	v_add_f32_e32 v220, v221, v220
	v_add_f32_e32 v221, v62, v78
	v_add_f32_e32 v220, v221, v220
	v_add_f32_e32 v221, v63, v79
	v_add_f32_e32 v220, v221, v220
	v_add_f32_e32 v197, v197, v220
	s_mul_i32 s54, s57, 0x4400
	v_add_u32_e32 v218, s54, v175
	ds_read_b128 v[200:203], v177 offset:16384
	ds_read_b128 v[204:207], v177 offset:20480
	ds_read_b128 v[208:211], v194 offset:16384
	ds_read_b128 v[212:215], v194 offset:20480
	ds_read_b128 v[226:229], v195 offset:16384
	ds_read_b128 v[230:233], v195 offset:20480
	ds_read_b128 v[234:237], v196 offset:16384
	ds_read_b128 v[238:241], v196 offset:20480
	s_setprio 1
	s_waitcnt lgkmcnt(7)
	v_mfma_f32_32x32x16_bf16 v[80:95], v[200:203], v[128:131], v[32:47]
	s_waitcnt lgkmcnt(6)
	v_mfma_f32_32x32x16_bf16 v[96:111], v[204:207], v[128:131], v[32:47]
	s_mul_i32 s55, s51, 0x4400
	ds_read_b128 v[200:203], v218 offset:32768
	s_waitcnt lgkmcnt(6)
	v_mfma_f32_32x32x16_bf16 v[80:95], v[208:211], v[132:135], v[80:95]
	v_add_u32_e32 v219, s55, v192
	ds_read_b128 v[204:207], v218 offset:41472
	s_waitcnt lgkmcnt(6)
	v_mfma_f32_32x32x16_bf16 v[96:111], v[212:215], v[132:135], v[96:111]
	s_add_i32 s54, s26, s50
	ds_read_b128 v[208:211], v218 offset:32800
	s_waitcnt lgkmcnt(6)
	v_mfma_f32_32x32x16_bf16 v[80:95], v[226:229], v[136:139], v[80:95]
	s_add_i32 s22, s56, 3
	ds_read_b128 v[212:215], v218 offset:41504
	s_waitcnt lgkmcnt(6)
	v_mfma_f32_32x32x16_bf16 v[96:111], v[230:233], v[136:139], v[96:111]
	s_nop 0
	ds_read_b128 v[226:229], v218 offset:32832
	s_waitcnt lgkmcnt(6)
	v_mfma_f32_32x32x16_bf16 v[80:95], v[234:237], v[140:143], v[80:95]
	s_nop 0
	ds_read_b128 v[230:233], v218 offset:41536
	s_waitcnt vmcnt(2)
	ds_write_b128 v191, v[112:115] offset:0
	ds_write_b128 v191, v[116:119] offset:8192
	s_waitcnt lgkmcnt(8)
	v_mfma_f32_32x32x16_bf16 v[96:111], v[238:241], v[140:143], v[96:111]
	s_nop 0
	ds_read_b128 v[234:237], v218 offset:32864
	s_waitcnt vmcnt(0)
	ds_write_b64 v219, v[120:121] offset:32768
	ds_write_b64 v219, v[122:123] offset:32784
	ds_read_b128 v[238:241], v218 offset:41568
	ds_write_b64 v219, v[124:125] offset:41472
	ds_write_b64 v219, v[126:127] offset:41488
	s_waitcnt lgkmcnt(13)
	v_mfma_f32_32x32x16_bf16 v[0:15], v[200:203], v[148:151], v[0:15]
	s_cmp_lt_i32 s22, s48
	s_cbranch_scc0 .Lat1_A_nok
	s_add_i32 s30, s54, 0x180
	s_ashr_i32 s31, s30, 31
	s_lshl_b64 s[30:31], s[30:31], 8
	v_lshl_add_u64 v[184:185], v[180:181], 0, s[30:31]
	global_load_dwordx4 v[112:115], v[184:185], off
	s_add_i32 s30, s54, 0x1c0
	s_ashr_i32 s31, s30, 31
	s_lshl_b64 s[30:31], s[30:31], 8
	v_lshl_add_u64 v[184:185], v[180:181], 0, s[30:31]
	global_load_dwordx4 v[116:119], v[184:185], off
.Lat1_A_nok:
	s_waitcnt lgkmcnt(12)
	v_mfma_f32_32x32x16_bf16 v[16:31], v[204:207], v[148:151], v[16:31]
	s_add_i32 s58, s54, 0x100
	s_ashr_i32 s59, s58, 31
	s_lshl_b64 s[58:59], s[58:59], 1
	v_lshl_add_u64 v[184:185], v[182:183], 0, s[58:59]
	global_load_dwordx4 v[120:123], v[184:185], off
	s_waitcnt lgkmcnt(11)
	v_mfma_f32_32x32x16_bf16 v[0:15], v[208:211], v[156:159], v[0:15]
	s_add_u32 s58, s58, 0x84000
	s_addc_u32 s59, s59, 0
	v_lshl_add_u64 v[184:185], v[182:183], 0, s[58:59]
	global_load_dwordx4 v[124:127], v[184:185], off
	s_waitcnt lgkmcnt(10)
	v_mfma_f32_32x32x16_bf16 v[16:31], v[212:215], v[156:159], v[16:31]
	s_waitcnt lgkmcnt(9)
	v_mfma_f32_32x32x16_bf16 v[0:15], v[226:229], v[152:155], v[0:15]
	s_waitcnt lgkmcnt(8)
	v_mfma_f32_32x32x16_bf16 v[16:31], v[230:233], v[152:155], v[16:31]
	s_waitcnt lgkmcnt(5)
	v_mfma_f32_32x32x16_bf16 v[0:15], v[234:237], v[144:147], v[0:15]
	s_waitcnt lgkmcnt(2)
	v_mfma_f32_32x32x16_bf16 v[16:31], v[238:241], v[144:147], v[16:31]
	s_setprio 0
	v_cvt_pk_bf16_f32 v148, v64, v65
	v_cvt_pk_bf16_f32 v149, v66, v67
	v_cvt_pk_bf16_f32 v150, v68, v69
	v_cvt_pk_bf16_f32 v151, v70, v71
	v_cvt_pk_bf16_f32 v156, v72, v73
	v_cvt_pk_bf16_f32 v157, v74, v75
	v_cvt_pk_bf16_f32 v158, v76, v77
	v_cvt_pk_bf16_f32 v159, v78, v79
	v_cvt_pk_bf16_f32 v152, v48, v49
	v_cvt_pk_bf16_f32 v153, v50, v51
	v_cvt_pk_bf16_f32 v154, v52, v53
	v_cvt_pk_bf16_f32 v155, v54, v55
	v_cvt_pk_bf16_f32 v144, v56, v57
	v_cvt_pk_bf16_f32 v145, v58, v59
	v_cvt_pk_bf16_f32 v146, v60, v61
	v_cvt_pk_bf16_f32 v147, v62, v63
	v_max3_f32 v242, v80, v81, v82
	v_max3_f32 v242, v242, v83, v84
	v_max3_f32 v242, v242, v85, v86
	v_max3_f32 v242, v242, v87, v88
	v_max3_f32 v242, v242, v89, v90
	v_max3_f32 v242, v242, v91, v92
	v_max3_f32 v242, v242, v93, v94
	v_max3_f32 v242, v242, v95, v96
	v_max3_f32 v242, v242, v97, v98
	v_max3_f32 v242, v242, v99, v100
	v_max3_f32 v242, v242, v101, v102
	v_max3_f32 v242, v242, v103, v104
	v_max3_f32 v242, v242, v105, v106
	v_max3_f32 v242, v242, v107, v108
	v_max3_f32 v242, v242, v109, v110
	v_max_f32_e32 v242, v242, v111
	v_cmp_lt_f32_e32 vcc, 0x41000000, v242
	s_add_i32 s53, s53, 0x4000
	s_mov_b32 s57, s52
	s_mov_b32 s52, s51
	s_add_i32 s22, s51, 1
	s_cmp_lg_u32 s51, 2
	s_cselect_b32 s51, s22, 0
	s_add_i32 s56, s56, 1
	s_addk_i32 s50, 0x80
	s_waitcnt lgkmcnt(0)
	s_barrier
	s_cbranch_vccnz .Lat_exitA
; __device__ __forceinline__ void attn_unit(KP P, LAS unsigned char* lds, int l, int tid, int b, int hh, int q0, bool lat) {
;     ...
;         if (__any(pend != 0.f)) { S0 = S0 - pend; S1 = S1 - pend; }
;         AT_QK_LD((s + 1) & 1);
;         __builtin_amdgcn_sched_barrier(0);
;         __builtin_amdgcn_s_setprio(1); AT_QK_MMA(N0, N1); __builtin_amdgcn_s_setprio(0);
;         AT_PV_LD(vs_prev);
;         __builtin_amdgcn_sched_barrier(0);
;         __builtin_amdgcn_s_setprio(1); AT_PV_MMA(); __builtin_amdgcn_s_setprio(0);
;         __builtin_amdgcn_sched_barrier(0);
;         float rm = __builtin_fmaxf(__builtin_fmaxf(S0[0], S1[0]), S0[1]);
; #pragma unroll
;         for (int r = 1; r < 16; ++r) rm = __builtin_fmaxf(__builtin_fmaxf(rm, S1[r]), r < 15 ? S0[r + 1] : S1[r]);
;         { const auto rr = __builtin_amdgcn_permlane32_swap(__float_as_uint(rm), __float_as_uint(rm), false, false); rm = fmaxf(__uint_as_float(rr[0]), __uint_as_float(rr[1])); }
;         float alpha = 1.f; pend = 0.f;
;         if (s == 0 || __any(rm > AT_THR)) {
;             const float dl = s == 0 ? rm : fmaxf(rm, 0.f);
;             S0 = S0 - dl; S1 = S1 - dl; negm = negm - dl; m += dl; pend = dl;
;             alpha = __builtin_amdgcn_exp2f(-dl); lsum *= alpha;
;         }
;         float ps = 0.f;
; #pragma unroll
;         for (int r = 0; r < 16; ++r) { S0[r] = __builtin_amdgcn_exp2f(S0[r]); S1[r] = __builtin_amdgcn_exp2f(S1[r]); ps += S0[r] + S1[r]; }
;         lsum += ps;
; #pragma unroll
;         for (int sl = 0; sl < 4; ++sl) { const int rb = 8 * (sl & 1);
;             if (sl < 2) pp[sl] = (u32x4_t){cvtpk(S0[rb], S0[rb + 1]), cvtpk(S0[rb + 2], S0[rb + 3]), cvtpk(S0[rb + 4], S0[rb + 5]), cvtpk(S0[rb + 6], S0[rb + 7])};
;             else pp[sl] = (u32x4_t){cvtpk(S1[rb], S1[rb + 1]), cvtpk(S1[rb + 2], S1[rb + 3]), cvtpk(S1[rb + 4], S1[rb + 5]), cvtpk(S1[rb + 6], S1[rb + 7])}; }
;         __builtin_amdgcn_sched_barrier(0);
;         if (__any(alpha != 1.f)) {
; #pragma unroll
;             for (int r = 0; r < 16; ++r) { O0[r] *= alpha; O1[r] *= alpha; } }
;         if (s + 2 < nsteps) AT_STOREK(s & 1);
;         if (s + 1 < nsteps) AT_STOREV(vs_next);
;         __syncthreads();
;         S0 = N0; S1 = N1;
;         vs_prev = vs_cur; vs_cur = vs_next; vs_next = vs_next == 2 ? 0 : vs_next + 1;
;     }
.Lat1_B:
	v_exp_f32_e32 v80, v80
	v_exp_f32_e32 v96, v96
	v_exp_f32_e32 v81, v81
	v_exp_f32_e32 v97, v97
	v_exp_f32_e32 v82, v82
	v_exp_f32_e32 v98, v98
	v_exp_f32_e32 v83, v83
	v_exp_f32_e32 v99, v99
	v_add_f32_e32 v220, v96, v80
	v_exp_f32_e32 v84, v84
	v_exp_f32_e32 v100, v100
	v_add_f32_e32 v221, v97, v81
	v_add_f32_e32 v220, v221, v220
	v_exp_f32_e32 v85, v85
	v_exp_f32_e32 v101, v101
	v_add_f32_e32 v221, v98, v82
	v_add_f32_e32 v220, v221, v220
	v_exp_f32_e32 v86, v86
	v_exp_f32_e32 v102, v102
	v_add_f32_e32 v221, v99, v83
	v_add_f32_e32 v220, v221, v220
	v_exp_f32_e32 v87, v87
	v_exp_f32_e32 v103, v103
	v_add_f32_e32 v221, v100, v84
	v_add_f32_e32 v220, v221, v220
	v_exp_f32_e32 v88, v88
	v_exp_f32_e32 v104, v104
	v_add_f32_e32 v221, v101, v85
	v_add_f32_e32 v220, v221, v220
	v_exp_f32_e32 v89, v89
	v_exp_f32_e32 v105, v105
	v_add_f32_e32 v221, v102, v86
	v_add_f32_e32 v220, v221, v220
	v_exp_f32_e32 v90, v90
	v_exp_f32_e32 v106, v106
	v_add_f32_e32 v221, v103, v87
	v_add_f32_e32 v220, v221, v220
	v_exp_f32_e32 v91, v91
	v_exp_f32_e32 v107, v107
	v_add_f32_e32 v221, v104, v88
	v_add_f32_e32 v220, v221, v220
	v_exp_f32_e32 v92, v92
	v_exp_f32_e32 v108, v108
	v_add_f32_e32 v221, v105, v89
	v_add_f32_e32 v220, v221, v220
	v_exp_f32_e32 v93, v93
	v_exp_f32_e32 v109, v109
	v_add_f32_e32 v221, v106, v90
	v_add_f32_e32 v220, v221, v220
	v_exp_f32_e32 v94, v94
	v_exp_f32_e32 v110, v110
	v_add_f32_e32 v221, v107, v91
	v_add_f32_e32 v220, v221, v220
	v_exp_f32_e32 v95, v95
	v_exp_f32_e32 v111, v111
	v_add_f32_e32 v221, v108, v92
	v_add_f32_e32 v220, v221, v220
	v_add_f32_e32 v221, v109, v93
	v_add_f32_e32 v220, v221, v220
	v_add_f32_e32 v221, v110, v94
	v_add_f32_e32 v220, v221, v220
	v_add_f32_e32 v221, v111, v95
	v_add_f32_e32 v220, v221, v220
	v_add_f32_e32 v197, v197, v220
	s_mul_i32 s54, s57, 0x4400
	v_add_u32_e32 v218, s54, v175
	ds_read_b128 v[200:203], v177 offset:0
	ds_read_b128 v[204:207], v177 offset:4096
	ds_read_b128 v[208:211], v194 offset:0
	ds_read_b128 v[212:215], v194 offset:4096
	ds_read_b128 v[226:229], v195 offset:0
	ds_read_b128 v[230:233], v195 offset:4096
	ds_read_b128 v[234:237], v196 offset:0
	ds_read_b128 v[238:241], v196 offset:4096
	s_setprio 1
	s_waitcnt lgkmcnt(7)
	v_mfma_f32_32x32x16_bf16 v[64:79], v[200:203], v[128:131], v[32:47]
	s_waitcnt lgkmcnt(6)
	v_mfma_f32_32x32x16_bf16 v[48:63], v[204:207], v[128:131], v[32:47]
	s_mul_i32 s55, s51, 0x4400
	ds_read_b128 v[200:203], v218 offset:32768
	s_waitcnt lgkmcnt(6)
	v_mfma_f32_32x32x16_bf16 v[64:79], v[208:211], v[132:135], v[64:79]
	v_add_u32_e32 v219, s55, v192
	ds_read_b128 v[204:207], v218 offset:41472
	s_waitcnt lgkmcnt(6)
	v_mfma_f32_32x32x16_bf16 v[48:63], v[212:215], v[132:135], v[48:63]
	s_add_i32 s54, s26, s50
	ds_read_b128 v[208:211], v218 offset:32800
	s_waitcnt lgkmcnt(6)
	v_mfma_f32_32x32x16_bf16 v[64:79], v[226:229], v[136:139], v[64:79]
	s_add_i32 s22, s56, 3
	ds_read_b128 v[212:215], v218 offset:41504
	s_waitcnt lgkmcnt(6)
	v_mfma_f32_32x32x16_bf16 v[48:63], v[230:233], v[136:139], v[48:63]
	s_nop 0
	ds_read_b128 v[226:229], v218 offset:32832
	s_waitcnt lgkmcnt(6)
	v_mfma_f32_32x32x16_bf16 v[64:79], v[234:237], v[140:143], v[64:79]
	s_nop 0
	ds_read_b128 v[230:233], v218 offset:41536
	s_waitcnt vmcnt(2)
	ds_write_b128 v191, v[112:115] offset:16384
	ds_write_b128 v191, v[116:119] offset:24576
	s_waitcnt lgkmcnt(8)
	v_mfma_f32_32x32x16_bf16 v[48:63], v[238:241], v[140:143], v[48:63]
	s_nop 0
	ds_read_b128 v[234:237], v218 offset:32864
	s_waitcnt vmcnt(0)
	ds_write_b64 v219, v[120:121] offset:32768
	ds_write_b64 v219, v[122:123] offset:32784
	ds_read_b128 v[238:241], v218 offset:41568
	ds_write_b64 v219, v[124:125] offset:41472
	ds_write_b64 v219, v[126:127] offset:41488
	s_waitcnt lgkmcnt(13)
	v_mfma_f32_32x32x16_bf16 v[0:15], v[200:203], v[148:151], v[0:15]
	s_cmp_lt_i32 s22, s48
	s_cbranch_scc0 .Lat1_B_nok
	s_add_i32 s30, s54, 0x180
	s_ashr_i32 s31, s30, 31
	s_lshl_b64 s[30:31], s[30:31], 8
	v_lshl_add_u64 v[184:185], v[180:181], 0, s[30:31]
	global_load_dwordx4 v[112:115], v[184:185], off
	s_add_i32 s30, s54, 0x1c0
	s_ashr_i32 s31, s30, 31
	s_lshl_b64 s[30:31], s[30:31], 8
	v_lshl_add_u64 v[184:185], v[180:181], 0, s[30:31]
	global_load_dwordx4 v[116:119], v[184:185], off
.Lat1_B_nok:
	s_waitcnt lgkmcnt(12)
	v_mfma_f32_32x32x16_bf16 v[16:31], v[204:207], v[148:151], v[16:31]
	s_add_i32 s58, s54, 0x100
	s_ashr_i32 s59, s58, 31
	s_lshl_b64 s[58:59], s[58:59], 1
	v_lshl_add_u64 v[184:185], v[182:183], 0, s[58:59]
	global_load_dwordx4 v[120:123], v[184:185], off
	s_waitcnt lgkmcnt(11)
	v_mfma_f32_32x32x16_bf16 v[0:15], v[208:211], v[156:159], v[0:15]
	s_add_u32 s58, s58, 0x84000
	s_addc_u32 s59, s59, 0
	v_lshl_add_u64 v[184:185], v[182:183], 0, s[58:59]
	global_load_dwordx4 v[124:127], v[184:185], off
	s_waitcnt lgkmcnt(10)
	v_mfma_f32_32x32x16_bf16 v[16:31], v[212:215], v[156:159], v[16:31]
	s_waitcnt lgkmcnt(9)
	v_mfma_f32_32x32x16_bf16 v[0:15], v[226:229], v[152:155], v[0:15]
	s_waitcnt lgkmcnt(8)
	v_mfma_f32_32x32x16_bf16 v[16:31], v[230:233], v[152:155], v[16:31]
	s_waitcnt lgkmcnt(5)
	v_mfma_f32_32x32x16_bf16 v[0:15], v[234:237], v[144:147], v[0:15]
	s_waitcnt lgkmcnt(2)
	v_mfma_f32_32x32x16_bf16 v[16:31], v[238:241], v[144:147], v[16:31]
	s_setprio 0
	v_cvt_pk_bf16_f32 v148, v80, v81
	v_cvt_pk_bf16_f32 v149, v82, v83
	v_cvt_pk_bf16_f32 v150, v84, v85
	v_cvt_pk_bf16_f32 v151, v86, v87
	v_cvt_pk_bf16_f32 v156, v88, v89
	v_cvt_pk_bf16_f32 v157, v90, v91
	v_cvt_pk_bf16_f32 v158, v92, v93
	v_cvt_pk_bf16_f32 v159, v94, v95
	v_cvt_pk_bf16_f32 v152, v96, v97
	v_cvt_pk_bf16_f32 v153, v98, v99
	v_cvt_pk_bf16_f32 v154, v100, v101
	v_cvt_pk_bf16_f32 v155, v102, v103
	v_cvt_pk_bf16_f32 v144, v104, v105
	v_cvt_pk_bf16_f32 v145, v106, v107
	v_cvt_pk_bf16_f32 v146, v108, v109
	v_cvt_pk_bf16_f32 v147, v110, v111
	v_max3_f32 v242, v64, v65, v66
	v_max3_f32 v242, v242, v67, v68
	v_max3_f32 v242, v242, v69, v70
	v_max3_f32 v242, v242, v71, v72
	v_max3_f32 v242, v242, v73, v74
	v_max3_f32 v242, v242, v75, v76
	v_max3_f32 v242, v242, v77, v78
	v_max3_f32 v242, v242, v79, v48
	v_max3_f32 v242, v242, v49, v50
	v_max3_f32 v242, v242, v51, v52
	v_max3_f32 v242, v242, v53, v54
	v_max3_f32 v242, v242, v55, v56
	v_max3_f32 v242, v242, v57, v58
	v_max3_f32 v242, v242, v59, v60
	v_max3_f32 v242, v242, v61, v62
	v_max_f32_e32 v242, v242, v63
	v_cmp_lt_f32_e32 vcc, 0x41000000, v242
	s_add_i32 s53, s53, 0x4000
	s_mov_b32 s57, s52
	s_mov_b32 s52, s51
	s_add_i32 s22, s51, 1
	s_cmp_lg_u32 s51, 2
	s_cselect_b32 s51, s22, 0
	s_add_i32 s56, s56, 1
	s_addk_i32 s50, 0x80
	s_waitcnt lgkmcnt(0)
	s_barrier
	s_cbranch_vccnz .Lat_exitB
	s_cmp_lt_u32 s56, 63
	s_cbranch_scc1 .Lat1_A
	s_branch .Lat_exitB
